# attention units: next ticket read with ds_read (lgkmcnt only) so the unit-end wait no longer covers the output stores; output stores and MoBA ticket atomic as global ops
# speedup vs baseline: 1.0094x; 1.0024x over previous
; __device__ __forceinline__ int crow(int r,int hi){return (r&3)+8*(r>>2)+4*hi;}
; __device__ __forceinline__ unsigned cvtpk_s(float lo,float hi){f32x2_t v={lo,hi};bf16x2_t b=__builtin_convertvector(v,bf16x2_t);return __builtin_bit_cast(unsigned,b);}
; template<int THRL,int MODE,int DM,bool DRY=false> __device__ __forceinline__ void attn_unit(int b,int h,int qb,const bf16*Q,const bf16*__restrict__ K,const bf16*__restrict__ V,bf16*O,const bf16*__restrict__ Z,const float*__restrict__ XP,const int*__restrict__ TS,volatile unsigned*lw,unsigned nxt,cha ...
;     ...
;   if(hi==0)wsf[32+r32]=l_reg;asm volatile("s_waitcnt lgkmcnt(0)":::"memory");
;   float rli[16];
;   #pragma unroll
;   for(int r=0;r<16;++r)rli[r]=__builtin_amdgcn_rcpf(wsf[32+crow(r,hi)]);
;   bf16*Ow=O+(rowbase+q0+wid*QBLK)*DM+h*D;
;   { bf16*stg=(bf16*)(shm+LDS_OST)+wid*2048;
;     #pragma unroll
;     for(int r=0;r<16;++r){const int orow=crow(r,hi);
;       #pragma unroll
;       for(int d0=0;d0<2;++d0)stg[orow*64+d0*32+r32]=__float2bfloat16(o[d0][r]*rli[r]);}
;     asm volatile("s_waitcnt lgkmcnt(0)":::"memory");
;     #pragma unroll
;     for(int i=0;i<4;++i){const int row=i*8+(lane>>3),ch=lane&7; const u32x4 v=*(const u32x4*)(stg+row*64+ch*8); const u32x4 zv=zpre[i]; u32x4 ov;
;       #pragma unroll
;       for(int e=0;e<4;++e){ const float o0=__uint_as_float(v[e]<<16),o1=__uint_as_float(v[e]&0xffff0000u),z0=__uint_as_float(zv[e]<<16),z1=__uint_as_float(zv[e]&0xffff0000u);
;         ov[e]=cvtpk_s(o0*z0*__builtin_amdgcn_rcpf(1.f+__expf(-z0)),o1*z1*__builtin_amdgcn_rcpf(1.f+__expf(-z1))); }
;       if(!DRY||ov[0]==0x7fc12345u)ATTN_STORE16(Ow+(long)row*DM+ch*8,ov);} }
.LBB0_891:
	s_or_b64 exec, exec, s[8:9]
	s_waitcnt lgkmcnt(0)
	ds_read_b128 v[48:51], v98 offset:49280
	ds_read_b128 v[52:55], v98 offset:49312
	s_lshl_b32 s8, s65, 12
	s_add_i32 s8, s8, 0
	v_lshlrev_b32_e32 v64, 1, v237
	s_waitcnt lgkmcnt(0)
	v_rcp_f32_e32 v56, v48
	v_rcp_f32_e32 v57, v49
	v_lshlrev_b32_e32 v65, 9, v238
	v_add3_u32 v64, s8, v64, v65
	v_mul_f32_e32 v16, v16, v56
	v_cvt_pk_bf16_f32 v16, v16, s0
	v_rcp_f32_e32 v58, v50
	v_rcp_f32_e32 v59, v51
	v_rcp_f32_e32 v60, v52
	ds_read_b128 v[48:51], v98 offset:49344
	v_rcp_f32_e32 v61, v53
	v_rcp_f32_e32 v62, v54
	v_rcp_f32_e32 v63, v55
	ds_read_b128 v[52:55], v98 offset:49376
	ds_write_b16 v64, v16 offset:51200
	v_mul_f32_e32 v16, v32, v56
	v_cvt_pk_bf16_f32 v16, v16, s0
	ds_write_b16 v64, v16 offset:51264
	v_mul_f32_e32 v16, v17, v57
	v_cvt_pk_bf16_f32 v16, v16, s0
	ds_write_b16 v64, v16 offset:51328
	v_mul_f32_e32 v16, v33, v57
	v_cvt_pk_bf16_f32 v16, v16, s0
	ds_write_b16 v64, v16 offset:51392
	v_mul_f32_e32 v16, v18, v58
	v_cvt_pk_bf16_f32 v16, v16, s0
	ds_write_b16 v64, v16 offset:51456
	v_mul_f32_e32 v16, v34, v58
	v_cvt_pk_bf16_f32 v16, v16, s0
	ds_write_b16 v64, v16 offset:51520
	v_mul_f32_e32 v16, v19, v59
	v_cvt_pk_bf16_f32 v16, v16, s0
	ds_write_b16 v64, v16 offset:51584
	v_mul_f32_e32 v16, v35, v59
	v_cvt_pk_bf16_f32 v16, v16, s0
	ds_write_b16 v64, v16 offset:51648
	v_mul_f32_e32 v16, v20, v60
	v_cvt_pk_bf16_f32 v16, v16, s0
	ds_write_b16 v64, v16 offset:52224
	v_mul_f32_e32 v16, v36, v60
	v_cvt_pk_bf16_f32 v16, v16, s0
	ds_write_b16 v64, v16 offset:52288
	v_mul_f32_e32 v16, v21, v61
	v_cvt_pk_bf16_f32 v16, v16, s0
	ds_write_b16 v64, v16 offset:52352
	v_mul_f32_e32 v16, v37, v61
	v_cvt_pk_bf16_f32 v16, v16, s0
	ds_write_b16 v64, v16 offset:52416
	v_mul_f32_e32 v16, v22, v62
	v_cvt_pk_bf16_f32 v16, v16, s0
	ds_write_b16 v64, v16 offset:52480
	v_mul_f32_e32 v16, v38, v62
	v_cvt_pk_bf16_f32 v16, v16, s0
	s_waitcnt lgkmcnt(0)
	v_rcp_f32_e32 v48, v48
	ds_write_b16 v64, v16 offset:52544
	v_mul_f32_e32 v16, v23, v63
	v_cvt_pk_bf16_f32 v16, v16, s0
	ds_write_b16 v64, v16 offset:52608
	v_mul_f32_e32 v16, v39, v63
	v_cvt_pk_bf16_f32 v16, v16, s0
	v_rcp_f32_e32 v49, v49
	ds_write_b16 v64, v16 offset:52672
	v_mul_f32_e32 v16, v24, v48
	v_cvt_pk_bf16_f32 v16, v16, s0
	ds_write_b16 v64, v16 offset:53248
	v_mul_f32_e32 v16, v40, v48
	v_cvt_pk_bf16_f32 v16, v16, s0
	v_rcp_f32_e32 v50, v50
	ds_write_b16 v64, v16 offset:53312
	v_mul_f32_e32 v16, v25, v49
	v_cvt_pk_bf16_f32 v16, v16, s0
	ds_write_b16 v64, v16 offset:53376
	v_mul_f32_e32 v16, v41, v49
	v_cvt_pk_bf16_f32 v16, v16, s0
	v_rcp_f32_e32 v51, v51
	ds_write_b16 v64, v16 offset:53440
	v_mul_f32_e32 v16, v26, v50
	v_cvt_pk_bf16_f32 v16, v16, s0
	ds_write_b16 v64, v16 offset:53504
	v_mul_f32_e32 v16, v42, v50
	v_cvt_pk_bf16_f32 v16, v16, s0
	v_rcp_f32_e32 v52, v52
	ds_write_b16 v64, v16 offset:53568
	v_mul_f32_e32 v16, v27, v51
	v_cvt_pk_bf16_f32 v16, v16, s0
	ds_write_b16 v64, v16 offset:53632
	v_mul_f32_e32 v16, v43, v51
	v_cvt_pk_bf16_f32 v16, v16, s0
	v_rcp_f32_e32 v53, v53
	ds_write_b16 v64, v16 offset:53696
	v_mul_f32_e32 v16, v28, v52
	v_cvt_pk_bf16_f32 v16, v16, s0
	ds_write_b16 v64, v16 offset:54272
	v_mul_f32_e32 v16, v44, v52
	v_cvt_pk_bf16_f32 v16, v16, s0
	v_rcp_f32_e32 v54, v54
	ds_write_b16 v64, v16 offset:54336
	v_mul_f32_e32 v16, v29, v53
	v_cvt_pk_bf16_f32 v16, v16, s0
	ds_write_b16 v64, v16 offset:54400
	v_mul_f32_e32 v16, v45, v53
	v_cvt_pk_bf16_f32 v16, v16, s0
	v_rcp_f32_e32 v55, v55
	ds_write_b16 v64, v16 offset:54464
	v_mul_f32_e32 v16, v30, v54
	v_cvt_pk_bf16_f32 v16, v16, s0
	ds_write_b16 v64, v16 offset:54528
	v_mul_f32_e32 v16, v46, v54
	v_cvt_pk_bf16_f32 v16, v16, s0
	ds_write_b16 v64, v16 offset:54592
	v_mul_f32_e32 v16, v31, v55
	v_cvt_pk_bf16_f32 v16, v16, s0
	ds_write_b16 v64, v16 offset:54656
	v_mul_f32_e32 v16, v47, v55
	v_cvt_pk_bf16_f32 v16, v16, s0
	ds_write_b16 v64, v16 offset:54720
	v_lshlrev_b32_e32 v16, 7, v99
	s_waitcnt vmcnt(0)
	v_lshlrev_b32_e32 v20, 16, v92
	v_add3_u32 v30, s8, v222, v16
	v_and_b32_e32 v23, 0xffff0000, v92
	v_mul_f32_e32 v16, 0xbfb8aa3b, v20
	v_exp_f32_e32 v21, v16
	v_mul_f32_e32 v16, 0xbfb8aa3b, v23
	v_exp_f32_e32 v22, v16
	s_waitcnt lgkmcnt(0)
	ds_read_b128 v[16:19], v30 offset:51200
	v_add_f32_e32 v21, 1.0, v21
	v_rcp_f32_e32 v26, v21
	v_add_f32_e32 v21, 1.0, v22
	v_rcp_f32_e32 v27, v21
	s_waitcnt lgkmcnt(0)
	v_and_b32_e32 v21, 0xffff0000, v16
	v_lshlrev_b32_e32 v22, 16, v16
	v_pk_mul_f32 v[20:21], v[22:23], v[20:21]
	v_lshlrev_b32_e32 v22, 16, v93
	v_pk_mul_f32 v[20:21], v[26:27], v[20:21]
	v_and_b32_e32 v27, 0xffff0000, v93
	v_mul_f32_e32 v16, 0xbfb8aa3b, v22
	v_exp_f32_e32 v16, v16
	v_mul_f32_e32 v23, 0xbfb8aa3b, v27
	v_exp_f32_e32 v23, v23
	v_lshlrev_b32_e32 v26, 16, v17
	v_add_f32_e32 v16, 1.0, v16
	v_rcp_f32_e32 v28, v16
	v_add_f32_e32 v16, 1.0, v23
	v_and_b32_e32 v23, 0xffff0000, v17
	v_rcp_f32_e32 v29, v16
	v_pk_mul_f32 v[16:17], v[26:27], v[22:23]
	v_lshlrev_b32_e32 v22, 16, v94
	v_cvt_pk_bf16_f32 v20, v20, v21
	v_and_b32_e32 v27, 0xffff0000, v94
	v_mul_f32_e32 v21, 0xbfb8aa3b, v22
	v_exp_f32_e32 v23, v21
	v_mul_f32_e32 v21, 0xbfb8aa3b, v27
	v_exp_f32_e32 v26, v21
	v_pk_mul_f32 v[16:17], v[28:29], v[16:17]
	v_and_b32_e32 v29, 0xffff0000, v95
	v_cvt_pk_bf16_f32 v21, v16, v17
	v_add_f32_e32 v16, 1.0, v23
	v_add_f32_e32 v17, 1.0, v26
	v_rcp_f32_e32 v16, v16
	v_rcp_f32_e32 v17, v17
	v_and_b32_e32 v23, 0xffff0000, v18
	v_lshlrev_b32_e32 v26, 16, v18
	v_pk_mul_f32 v[22:23], v[26:27], v[22:23]
	v_lshlrev_b32_e32 v26, 16, v95
	v_pk_mul_f32 v[16:17], v[16:17], v[22:23]
	v_mul_f32_e32 v18, 0xbfb8aa3b, v26
	v_mul_f32_e32 v22, 0xbfb8aa3b, v29
	v_exp_f32_e32 v18, v18
	v_exp_f32_e32 v23, v22
	v_cvt_pk_bf16_f32 v22, v16, v17
	v_and_b32_e32 v27, 0xffff0000, v19
	v_add_f32_e32 v16, 1.0, v18
	v_add_f32_e32 v17, 1.0, v23
	v_rcp_f32_e32 v16, v16
	v_rcp_f32_e32 v17, v17
	v_lshlrev_b32_e32 v28, 16, v19
	v_pk_mul_f32 v[18:19], v[28:29], v[26:27]
	v_lshl_add_u64 v[24:25], s[58:59], 0, v[222:223]
	v_pk_mul_f32 v[16:17], v[16:17], v[18:19]
	v_mov_b32_e32 v97, v223
	v_cvt_pk_bf16_f32 v23, v16, v17
	v_lshl_add_u64 v[16:17], v[24:25], 0, v[96:97]
	global_store_dwordx4 v[16:17], v[20:23], off
	v_and_b32_e32 v25, 0xffff0000, v88
	s_cmp_lg_u32 s3, -1
	v_lshlrev_b32_e32 v22, 16, v88
	v_mul_f32_e32 v18, 0xbfb8aa3b, v22
	v_exp_f32_e32 v23, v18
	v_mul_f32_e32 v18, 0xbfb8aa3b, v25
	v_exp_f32_e32 v24, v18
	ds_read_b128 v[18:21], v30 offset:52224
	v_add_f32_e32 v23, 1.0, v23
	v_rcp_f32_e32 v26, v23
	v_add_f32_e32 v23, 1.0, v24
	v_rcp_f32_e32 v27, v23
	s_waitcnt lgkmcnt(0)
; __device__ __forceinline__ unsigned cvtpk_s(float lo,float hi){f32x2_t v={lo,hi};bf16x2_t b=__builtin_convertvector(v,bf16x2_t);return __builtin_bit_cast(unsigned,b);}
; #define BAR_LDS() asm volatile("s_waitcnt lgkmcnt(0)\n\ts_barrier" ::: "memory")
; template<int THRL,int MODE,int DM,bool DRY=false> __device__ __forceinline__ void attn_unit(int b,int h,int qb,const bf16*Q,const bf16*__restrict__ K,const bf16*__restrict__ V,bf16*O,const bf16*__restrict__ Z,const float*__restrict__ XP,const int*__restrict__ TS,volatile unsigned*lw,unsigned nxt,cha ...
;     ...
;     for(int i=0;i<4;++i){const int row=i*8+(lane>>3),ch=lane&7; const u32x4 v=*(const u32x4*)(stg+row*64+ch*8); const u32x4 zv=zpre[i]; u32x4 ov;
;       #pragma unroll
;       for(int e=0;e<4;++e){ const float o0=__uint_as_float(v[e]<<16),o1=__uint_as_float(v[e]&0xffff0000u),z0=__uint_as_float(zv[e]<<16),z1=__uint_as_float(zv[e]&0xffff0000u);
;         ov[e]=cvtpk_s(o0*z0*__builtin_amdgcn_rcpf(1.f+__expf(-z0)),o1*z1*__builtin_amdgcn_rcpf(1.f+__expf(-z1))); }
;       if(!DRY||ov[0]==0x7fc12345u)ATTN_STORE16(Ow+(long)row*DM+ch*8,ov);} }
;   asm volatile("s_waitcnt lgkmcnt(0)\n\ts_barrier":::"memory");
; template <bool DRY> __device__ __forceinline__ void moba_phase(const Args& A, char* lds, int vcu, int G) {
;     ...
;         unsigned nxt = 0u; if (tid == 0) nxt = atomicAdd(cnt, 1u);
;         const int qb = 7 - u / 128, bh = u % 128, b = bh >> 4, h = bh & 15;
;         attn_body::attn_unit<8, 0, LD0, DRY>(b, h, qb, (const attn_body::bf16*)(P0 + C0_Q), (const attn_body::bf16*)(P0 + C0_K), (const attn_body::bf16*)(P0 + C0_V), (attn_body::bf16*)(P0 + C0_Q),
;                                             (const attn_body::bf16*)(P0 + C0_ZB), kbar + (size_t)bh * 512, nullptr, lw, nxt, lds);
;         BAR_LDS();
;         u = __builtin_amdgcn_readfirstlane((int)lw[0]);
	v_and_b32_e32 v23, 0xffff0000, v18
	v_lshlrev_b32_e32 v24, 16, v18
	v_pk_mul_f32 v[22:23], v[24:25], v[22:23]
	v_lshlrev_b32_e32 v24, 16, v89
	v_pk_mul_f32 v[22:23], v[26:27], v[22:23]
	v_and_b32_e32 v27, 0xffff0000, v89
	v_mul_f32_e32 v18, 0xbfb8aa3b, v24
	v_exp_f32_e32 v25, v18
	v_mul_f32_e32 v18, 0xbfb8aa3b, v27
	v_exp_f32_e32 v26, v18
	v_cvt_pk_bf16_f32 v18, v22, v23
	v_add_f32_e32 v22, 1.0, v25
	v_rcp_f32_e32 v22, v22
	v_add_f32_e32 v23, 1.0, v26
	v_rcp_f32_e32 v23, v23
	v_and_b32_e32 v25, 0xffff0000, v19
	v_lshlrev_b32_e32 v26, 16, v19
	v_pk_mul_f32 v[24:25], v[26:27], v[24:25]
	v_and_b32_e32 v27, 0xffff0000, v90
	v_pk_mul_f32 v[22:23], v[22:23], v[24:25]
	v_lshlrev_b32_e32 v24, 16, v90
	v_mul_f32_e32 v19, 0xbfb8aa3b, v24
	v_exp_f32_e32 v25, v19
	v_mul_f32_e32 v19, 0xbfb8aa3b, v27
	v_exp_f32_e32 v26, v19
	v_cvt_pk_bf16_f32 v19, v22, v23
	v_add_f32_e32 v22, 1.0, v25
	v_rcp_f32_e32 v22, v22
	v_add_f32_e32 v23, 1.0, v26
	v_rcp_f32_e32 v23, v23
	v_and_b32_e32 v25, 0xffff0000, v20
	v_lshlrev_b32_e32 v26, 16, v20
	v_pk_mul_f32 v[24:25], v[26:27], v[24:25]
	v_and_b32_e32 v27, 0xffff0000, v91
	v_pk_mul_f32 v[22:23], v[22:23], v[24:25]
	v_lshlrev_b32_e32 v24, 16, v91
	v_mul_f32_e32 v20, 0xbfb8aa3b, v24
	v_exp_f32_e32 v25, v20
	v_mul_f32_e32 v20, 0xbfb8aa3b, v27
	v_exp_f32_e32 v26, v20
	v_cvt_pk_bf16_f32 v20, v22, v23
	v_add_f32_e32 v22, 1.0, v25
	v_rcp_f32_e32 v22, v22
	v_add_f32_e32 v23, 1.0, v26
	v_rcp_f32_e32 v23, v23
	v_and_b32_e32 v25, 0xffff0000, v21
	v_lshlrev_b32_e32 v26, 16, v21
	v_pk_mul_f32 v[24:25], v[26:27], v[24:25]
	s_cselect_b32 s8, s3, 0
	v_pk_mul_f32 v[22:23], v[22:23], v[24:25]
	v_and_b32_e32 v25, 0xffff0000, v84
	v_cvt_pk_bf16_f32 v21, v22, v23
	v_add_co_u32_e32 v22, vcc, s1, v16
	s_cselect_b32 s9, s27, 0
	s_nop 0
	v_addc_co_u32_e32 v23, vcc, 0, v17, vcc
	global_store_dwordx4 v[22:23], v[18:21], off
	v_lshlrev_b32_e32 v22, 16, v84
	s_nop 0
	v_mul_f32_e32 v18, 0xbfb8aa3b, v22
	v_exp_f32_e32 v23, v18
	v_mul_f32_e32 v18, 0xbfb8aa3b, v25
	v_exp_f32_e32 v24, v18
	ds_read_b128 v[18:21], v30 offset:53248
	v_add_f32_e32 v23, 1.0, v23
	v_rcp_f32_e32 v26, v23
	v_add_f32_e32 v23, 1.0, v24
	v_rcp_f32_e32 v27, v23
	s_waitcnt lgkmcnt(0)
	v_and_b32_e32 v23, 0xffff0000, v18
	v_lshlrev_b32_e32 v24, 16, v18
	v_pk_mul_f32 v[22:23], v[24:25], v[22:23]
	v_lshlrev_b32_e32 v24, 16, v85
	v_pk_mul_f32 v[22:23], v[26:27], v[22:23]
	v_and_b32_e32 v27, 0xffff0000, v85
	v_mul_f32_e32 v18, 0xbfb8aa3b, v24
	v_exp_f32_e32 v25, v18
	v_mul_f32_e32 v18, 0xbfb8aa3b, v27
	v_exp_f32_e32 v26, v18
	v_cvt_pk_bf16_f32 v18, v22, v23
	v_add_f32_e32 v22, 1.0, v25
	v_rcp_f32_e32 v22, v22
	v_add_f32_e32 v23, 1.0, v26
	v_rcp_f32_e32 v23, v23
	v_and_b32_e32 v25, 0xffff0000, v19
	v_lshlrev_b32_e32 v26, 16, v19
	v_pk_mul_f32 v[24:25], v[26:27], v[24:25]
	v_and_b32_e32 v27, 0xffff0000, v86
	v_pk_mul_f32 v[22:23], v[22:23], v[24:25]
	v_lshlrev_b32_e32 v24, 16, v86
	v_mul_f32_e32 v19, 0xbfb8aa3b, v24
	v_exp_f32_e32 v25, v19
	v_mul_f32_e32 v19, 0xbfb8aa3b, v27
	v_exp_f32_e32 v26, v19
	v_cvt_pk_bf16_f32 v19, v22, v23
	v_add_f32_e32 v22, 1.0, v25
	v_rcp_f32_e32 v22, v22
	v_add_f32_e32 v23, 1.0, v26
	v_rcp_f32_e32 v23, v23
	v_and_b32_e32 v25, 0xffff0000, v20
	v_lshlrev_b32_e32 v26, 16, v20
	v_pk_mul_f32 v[24:25], v[26:27], v[24:25]
	v_and_b32_e32 v27, 0xffff0000, v87
	v_pk_mul_f32 v[22:23], v[22:23], v[24:25]
	v_lshlrev_b32_e32 v24, 16, v87
	v_mul_f32_e32 v20, 0xbfb8aa3b, v24
	v_exp_f32_e32 v25, v20
	v_mul_f32_e32 v20, 0xbfb8aa3b, v27
	v_exp_f32_e32 v26, v20
	v_cvt_pk_bf16_f32 v20, v22, v23
	v_add_f32_e32 v22, 1.0, v25
	v_rcp_f32_e32 v22, v22
	v_add_f32_e32 v23, 1.0, v26
	v_rcp_f32_e32 v23, v23
	v_and_b32_e32 v25, 0xffff0000, v21
	v_lshlrev_b32_e32 v26, 16, v21
	v_pk_mul_f32 v[24:25], v[26:27], v[24:25]
	s_nop 0
	v_pk_mul_f32 v[22:23], v[22:23], v[24:25]
	v_and_b32_e32 v25, 0xffff0000, v80
	v_cvt_pk_bf16_f32 v21, v22, v23
	v_add_co_u32_e32 v22, vcc, s89, v16
	s_nop 1
	v_addc_co_u32_e32 v23, vcc, 0, v17, vcc
	global_store_dwordx4 v[22:23], v[18:21], off
	v_lshlrev_b32_e32 v22, 16, v80
	v_add_co_u32_e32 v16, vcc, s90, v16
	v_mul_f32_e32 v18, 0xbfb8aa3b, v22
	v_exp_f32_e32 v23, v18
	v_mul_f32_e32 v18, 0xbfb8aa3b, v25
	v_exp_f32_e32 v24, v18
	ds_read_b128 v[18:21], v30 offset:54272
	v_add_f32_e32 v23, 1.0, v23
	v_rcp_f32_e32 v26, v23
	v_add_f32_e32 v23, 1.0, v24
	v_rcp_f32_e32 v27, v23
	s_waitcnt lgkmcnt(0)
	v_and_b32_e32 v23, 0xffff0000, v18
	v_lshlrev_b32_e32 v24, 16, v18
	v_pk_mul_f32 v[22:23], v[24:25], v[22:23]
	v_lshlrev_b32_e32 v24, 16, v81
	v_pk_mul_f32 v[22:23], v[26:27], v[22:23]
	v_and_b32_e32 v27, 0xffff0000, v81
	v_mul_f32_e32 v18, 0xbfb8aa3b, v24
	v_exp_f32_e32 v25, v18
	v_mul_f32_e32 v18, 0xbfb8aa3b, v27
	v_exp_f32_e32 v26, v18
	v_cvt_pk_bf16_f32 v18, v22, v23
	v_add_f32_e32 v22, 1.0, v25
	v_rcp_f32_e32 v22, v22
	v_add_f32_e32 v23, 1.0, v26
	v_rcp_f32_e32 v23, v23
	v_and_b32_e32 v25, 0xffff0000, v19
	v_lshlrev_b32_e32 v26, 16, v19
	v_pk_mul_f32 v[24:25], v[26:27], v[24:25]
	v_and_b32_e32 v27, 0xffff0000, v82
	v_pk_mul_f32 v[22:23], v[22:23], v[24:25]
	v_lshlrev_b32_e32 v24, 16, v82
	v_mul_f32_e32 v19, 0xbfb8aa3b, v24
	v_exp_f32_e32 v25, v19
	v_mul_f32_e32 v19, 0xbfb8aa3b, v27
	v_exp_f32_e32 v26, v19
	v_cvt_pk_bf16_f32 v19, v22, v23
	v_add_f32_e32 v22, 1.0, v25
	v_rcp_f32_e32 v22, v22
	v_add_f32_e32 v23, 1.0, v26
	v_rcp_f32_e32 v23, v23
	v_and_b32_e32 v25, 0xffff0000, v20
	v_lshlrev_b32_e32 v26, 16, v20
	v_pk_mul_f32 v[24:25], v[26:27], v[24:25]
	v_and_b32_e32 v27, 0xffff0000, v83
	v_pk_mul_f32 v[22:23], v[22:23], v[24:25]
	v_lshlrev_b32_e32 v24, 16, v83
	v_mul_f32_e32 v20, 0xbfb8aa3b, v24
	v_exp_f32_e32 v25, v20
	v_mul_f32_e32 v20, 0xbfb8aa3b, v27
	v_exp_f32_e32 v26, v20
	v_cvt_pk_bf16_f32 v20, v22, v23
	v_add_f32_e32 v22, 1.0, v25
	v_rcp_f32_e32 v22, v22
	v_add_f32_e32 v23, 1.0, v26
	v_rcp_f32_e32 v23, v23
	v_and_b32_e32 v25, 0xffff0000, v21
	v_lshlrev_b32_e32 v26, 16, v21
	v_pk_mul_f32 v[24:25], v[26:27], v[24:25]
	v_addc_co_u32_e32 v17, vcc, 0, v17, vcc
	v_pk_mul_f32 v[22:23], v[22:23], v[24:25]
	s_nop 0
	v_cvt_pk_bf16_f32 v21, v22, v23
	global_store_dwordx4 v[16:17], v[18:21], off
	s_waitcnt lgkmcnt(0)
	s_barrier
	s_waitcnt lgkmcnt(0)
	s_barrier
	v_mov_b32_e32 v16, s8
	v_mov_b32_e32 v17, s9
	ds_read_b32 v16, v16
	s_waitcnt lgkmcnt(0)
	v_readfirstlane_b32 s10, v16
	s_cmpk_lt_i32 s10, 0x400
	s_cbranch_scc0 .LBB0_984
.LBB0_892:
	v_mov_b32_e32 v240, 0
	s_and_saveexec_b64 s[8:9], s[6:7]
	s_cbranch_execz .LBB0_894
	v_mov_b64_e32 v[16:17], s[22:23]
	global_atomic_add v240, v[16:17], v221, off sc0

; __device__ __forceinline__ int crow(int r,int hi){return (r&3)+8*(r>>2)+4*hi;}
; __device__ __forceinline__ unsigned cvtpk_s(float lo,float hi){f32x2_t v={lo,hi};bf16x2_t b=__builtin_convertvector(v,bf16x2_t);return __builtin_bit_cast(unsigned,b);}
; template<int THRL,int MODE,int DM,bool DRY=false> __device__ __forceinline__ void attn_unit(int b,int h,int qb,const bf16*Q,const bf16*__restrict__ K,const bf16*__restrict__ V,bf16*O,const bf16*__restrict__ Z,const float*__restrict__ XP,const int*__restrict__ TS,volatile unsigned*lw,unsigned nxt,cha ...
;     ...
;   if(hi==0)wsf[32+r32]=l_reg;asm volatile("s_waitcnt lgkmcnt(0)":::"memory");
;   float rli[16];
;   #pragma unroll
;   for(int r=0;r<16;++r)rli[r]=__builtin_amdgcn_rcpf(wsf[32+crow(r,hi)]);
;   bf16*Ow=O+(rowbase+q0+wid*QBLK)*DM+h*D;
;   { bf16*stg=(bf16*)(shm+LDS_OST)+wid*2048;
;     #pragma unroll
;     for(int r=0;r<16;++r){const int orow=crow(r,hi);
;       #pragma unroll
;       for(int d0=0;d0<2;++d0)stg[orow*64+d0*32+r32]=__float2bfloat16(o[d0][r]*rli[r]);}
;     asm volatile("s_waitcnt lgkmcnt(0)":::"memory");
;     #pragma unroll
;     for(int i=0;i<4;++i){const int row=i*8+(lane>>3),ch=lane&7; const u32x4 v=*(const u32x4*)(stg+row*64+ch*8); const u32x4 zv=zpre[i]; u32x4 ov;
;       #pragma unroll
;       for(int e=0;e<4;++e){ const float o0=__uint_as_float(v[e]<<16),o1=__uint_as_float(v[e]&0xffff0000u),z0=__uint_as_float(zv[e]<<16),z1=__uint_as_float(zv[e]&0xffff0000u);
;         ov[e]=cvtpk_s(o0*z0*__builtin_amdgcn_rcpf(1.f+__expf(-z0)),o1*z1*__builtin_amdgcn_rcpf(1.f+__expf(-z1))); }
;       if(!DRY||ov[0]==0x7fc12345u)ATTN_STORE16(Ow+(long)row*DM+ch*8,ov);} }
.LBB0_1435:
	s_or_b64 exec, exec, s[8:9]
	s_waitcnt lgkmcnt(0)
	ds_read_b128 v[32:35], v83 offset:49280
	ds_read_b128 v[36:39], v83 offset:49312
	s_lshl_b32 s8, s81, 12
	s_add_i32 s8, s8, 0
	v_lshlrev_b32_e32 v48, 1, v208
	s_waitcnt lgkmcnt(0)
	v_rcp_f32_e32 v40, v32
	v_rcp_f32_e32 v41, v33
	v_lshlrev_b32_e32 v49, 9, v209
	v_add3_u32 v48, s8, v48, v49
	v_mul_f32_e32 v0, v0, v40
	v_cvt_pk_bf16_f32 v0, v0, s0
	v_rcp_f32_e32 v42, v34
	v_rcp_f32_e32 v43, v35
	v_rcp_f32_e32 v44, v36
	ds_read_b128 v[32:35], v83 offset:49344
	v_rcp_f32_e32 v45, v37
	v_rcp_f32_e32 v46, v38
	v_rcp_f32_e32 v47, v39
	ds_read_b128 v[36:39], v83 offset:49376
	ds_write_b16 v48, v0 offset:51264
	v_mul_f32_e32 v0, v17, v41
	v_cvt_pk_bf16_f32 v0, v0, s0
	ds_write_b16 v48, v0 offset:51328
	v_mul_f32_e32 v0, v1, v41
	v_cvt_pk_bf16_f32 v0, v0, s0
	ds_write_b16 v48, v0 offset:51392
	v_mul_f32_e32 v0, v18, v42
	v_cvt_pk_bf16_f32 v0, v0, s0
	ds_write_b16 v48, v0 offset:51456
	v_mul_f32_e32 v0, v2, v42
	v_cvt_pk_bf16_f32 v0, v0, s0
	ds_write_b16 v48, v0 offset:51520
	v_mul_f32_e32 v0, v19, v43
	v_cvt_pk_bf16_f32 v0, v0, s0
	ds_write_b16 v48, v0 offset:51584
	v_mul_f32_e32 v0, v3, v43
	v_cvt_pk_bf16_f32 v0, v0, s0
	ds_write_b16 v48, v0 offset:51648
	v_mul_f32_e32 v0, v20, v44
	v_cvt_pk_bf16_f32 v0, v0, s0
	ds_write_b16 v48, v0 offset:52224
	v_mul_f32_e32 v0, v4, v44
	v_cvt_pk_bf16_f32 v0, v0, s0
	ds_write_b16 v48, v0 offset:52288
	v_mul_f32_e32 v0, v21, v45
	v_cvt_pk_bf16_f32 v0, v0, s0
	ds_write_b16 v48, v0 offset:52352
	v_mul_f32_e32 v0, v5, v45
	v_cvt_pk_bf16_f32 v0, v0, s0
	ds_write_b16 v48, v0 offset:52416
	v_mul_f32_e32 v0, v22, v46
	v_cvt_pk_bf16_f32 v0, v0, s0
	ds_write_b16 v48, v0 offset:52480
	v_mul_f32_e32 v0, v6, v46
	v_cvt_pk_bf16_f32 v0, v0, s0
	s_waitcnt lgkmcnt(0)
	v_rcp_f32_e32 v32, v32
	ds_write_b16 v48, v0 offset:52544
	v_mul_f32_e32 v0, v23, v47
	v_cvt_pk_bf16_f32 v0, v0, s0
	ds_write_b16 v48, v0 offset:52608
	v_mul_f32_e32 v0, v7, v47
	v_cvt_pk_bf16_f32 v0, v0, s0
	v_rcp_f32_e32 v33, v33
	ds_write_b16 v48, v0 offset:52672
	v_mul_f32_e32 v0, v24, v32
	v_cvt_pk_bf16_f32 v0, v0, s0
	ds_write_b16 v48, v0 offset:53248
	v_mul_f32_e32 v0, v8, v32
	v_cvt_pk_bf16_f32 v0, v0, s0
	v_rcp_f32_e32 v34, v34
	ds_write_b16 v48, v0 offset:53312
	v_mul_f32_e32 v0, v25, v33
	v_cvt_pk_bf16_f32 v0, v0, s0
	ds_write_b16 v48, v0 offset:53376
	v_mul_f32_e32 v0, v9, v33
	v_cvt_pk_bf16_f32 v0, v0, s0
	v_rcp_f32_e32 v35, v35
	ds_write_b16 v48, v0 offset:53440
	v_mul_f32_e32 v0, v26, v34
	v_cvt_pk_bf16_f32 v0, v0, s0
	ds_write_b16 v48, v0 offset:53504
	v_mul_f32_e32 v0, v10, v34
	v_cvt_pk_bf16_f32 v0, v0, s0
	v_rcp_f32_e32 v36, v36
	ds_write_b16 v48, v0 offset:53568
	v_mul_f32_e32 v0, v27, v35
	v_cvt_pk_bf16_f32 v0, v0, s0
	ds_write_b16 v48, v0 offset:53632
	v_mul_f32_e32 v0, v11, v35
	v_cvt_pk_bf16_f32 v0, v0, s0
	v_rcp_f32_e32 v37, v37
	ds_write_b16 v48, v0 offset:53696
	v_mul_f32_e32 v0, v28, v36
	v_cvt_pk_bf16_f32 v0, v0, s0
	ds_write_b16 v48, v0 offset:54272
	v_mul_f32_e32 v0, v12, v36
	v_cvt_pk_bf16_f32 v0, v0, s0
	v_rcp_f32_e32 v38, v38
	ds_write_b16 v48, v0 offset:54336
	v_mul_f32_e32 v0, v29, v37
	v_cvt_pk_bf16_f32 v0, v0, s0
	ds_write_b16 v48, v0 offset:54400
	v_mul_f32_e32 v0, v13, v37
	v_cvt_pk_bf16_f32 v0, v0, s0
	v_rcp_f32_e32 v39, v39
	ds_write_b16 v48, v0 offset:54464
	v_mul_f32_e32 v0, v30, v38
	v_cvt_pk_bf16_f32 v0, v0, s0
	ds_write_b16 v48, v0 offset:54528
	v_mul_f32_e32 v0, v14, v38
	v_cvt_pk_bf16_f32 v0, v0, s0
	ds_write_b16 v48, v0 offset:54592
	v_mul_f32_e32 v0, v31, v39
	v_cvt_pk_bf16_f32 v0, v0, s0
	ds_write_b16 v48, v0 offset:54656
	v_mul_f32_e32 v0, v15, v39
	v_cvt_pk_bf16_f32 v0, v0, s0
	ds_write_b16 v48, v0 offset:54720
	v_lshlrev_b32_e32 v0, 7, v84
	s_waitcnt vmcnt(0)
	v_lshlrev_b32_e32 v4, 16, v76
	v_mul_f32_e32 v16, v16, v40
	v_add3_u32 v14, s8, v192, v0
	v_and_b32_e32 v7, 0xffff0000, v76
	v_mul_f32_e32 v0, 0xbfb8aa3b, v4
	v_cvt_pk_bf16_f32 v16, v16, s0
	v_exp_f32_e32 v5, v0
	v_mul_f32_e32 v0, 0xbfb8aa3b, v7
	ds_write_b16 v48, v16 offset:51200
	v_exp_f32_e32 v6, v0
	s_waitcnt lgkmcnt(0)
	ds_read_b128 v[0:3], v14 offset:51200
	v_add_f32_e32 v5, 1.0, v5
	v_rcp_f32_e32 v10, v5
	v_add_f32_e32 v5, 1.0, v6
	v_rcp_f32_e32 v11, v5
	s_waitcnt lgkmcnt(0)
	v_and_b32_e32 v5, 0xffff0000, v0
	v_lshlrev_b32_e32 v6, 16, v0
	v_pk_mul_f32 v[4:5], v[6:7], v[4:5]
	v_lshlrev_b32_e32 v6, 16, v77
	v_pk_mul_f32 v[4:5], v[10:11], v[4:5]
	v_and_b32_e32 v11, 0xffff0000, v77
	v_mul_f32_e32 v0, 0xbfb8aa3b, v6
	v_exp_f32_e32 v0, v0
	v_mul_f32_e32 v7, 0xbfb8aa3b, v11
	v_exp_f32_e32 v7, v7
	v_lshlrev_b32_e32 v10, 16, v1
	v_add_f32_e32 v0, 1.0, v0
	v_rcp_f32_e32 v12, v0
	v_add_f32_e32 v0, 1.0, v7
	v_and_b32_e32 v7, 0xffff0000, v1
	v_rcp_f32_e32 v13, v0
	v_pk_mul_f32 v[0:1], v[10:11], v[6:7]
	v_lshlrev_b32_e32 v6, 16, v78
	v_cvt_pk_bf16_f32 v4, v4, v5
	v_and_b32_e32 v11, 0xffff0000, v78
	v_mul_f32_e32 v5, 0xbfb8aa3b, v6
	v_exp_f32_e32 v7, v5
	v_mul_f32_e32 v5, 0xbfb8aa3b, v11
	v_exp_f32_e32 v10, v5
	v_pk_mul_f32 v[0:1], v[12:13], v[0:1]
	v_and_b32_e32 v13, 0xffff0000, v79
	v_cvt_pk_bf16_f32 v5, v0, v1
	v_add_f32_e32 v0, 1.0, v7
	v_add_f32_e32 v1, 1.0, v10
	v_rcp_f32_e32 v0, v0
	v_rcp_f32_e32 v1, v1
	v_and_b32_e32 v7, 0xffff0000, v2
	v_lshlrev_b32_e32 v10, 16, v2
	v_pk_mul_f32 v[6:7], v[10:11], v[6:7]
	v_lshlrev_b32_e32 v10, 16, v79
	v_pk_mul_f32 v[0:1], v[0:1], v[6:7]
	v_mul_f32_e32 v2, 0xbfb8aa3b, v10
	v_mul_f32_e32 v6, 0xbfb8aa3b, v13
	v_exp_f32_e32 v2, v2
	v_exp_f32_e32 v7, v6
	v_cvt_pk_bf16_f32 v6, v0, v1
	v_and_b32_e32 v11, 0xffff0000, v3
	v_add_f32_e32 v0, 1.0, v2
	v_add_f32_e32 v1, 1.0, v7
	v_rcp_f32_e32 v0, v0
	v_rcp_f32_e32 v1, v1
	v_lshlrev_b32_e32 v12, 16, v3
	v_pk_mul_f32 v[2:3], v[12:13], v[10:11]
	v_lshl_add_u64 v[8:9], s[50:51], 0, v[192:193]
	v_pk_mul_f32 v[0:1], v[0:1], v[2:3]
	v_mov_b32_e32 v81, v193
	v_cvt_pk_bf16_f32 v7, v0, v1
	v_lshl_add_u64 v[0:1], v[8:9], 0, v[80:81]
	global_store_dwordx4 v[0:1], v[4:7], off
	v_and_b32_e32 v9, 0xffff0000, v72
	s_cmp_lg_u32 s3, -1
	v_lshlrev_b32_e32 v6, 16, v72
	v_mul_f32_e32 v2, 0xbfb8aa3b, v6
	v_exp_f32_e32 v7, v2
	v_mul_f32_e32 v2, 0xbfb8aa3b, v9
	v_exp_f32_e32 v8, v2
	ds_read_b128 v[2:5], v14 offset:52224
	v_add_f32_e32 v7, 1.0, v7
	v_rcp_f32_e32 v10, v7
	v_add_f32_e32 v7, 1.0, v8
	v_rcp_f32_e32 v11, v7
	s_waitcnt lgkmcnt(0)
; __device__ __forceinline__ unsigned cvtpk_s(float lo,float hi){f32x2_t v={lo,hi};bf16x2_t b=__builtin_convertvector(v,bf16x2_t);return __builtin_bit_cast(unsigned,b);}
; #define BAR_LDS() asm volatile("s_waitcnt lgkmcnt(0)\n\ts_barrier" ::: "memory")
; template<int THRL,int MODE,int DM,bool DRY=false> __device__ __forceinline__ void attn_unit(int b,int h,int qb,const bf16*Q,const bf16*__restrict__ K,const bf16*__restrict__ V,bf16*O,const bf16*__restrict__ Z,const float*__restrict__ XP,const int*__restrict__ TS,volatile unsigned*lw,unsigned nxt,cha ...
;     ...
;     for(int i=0;i<4;++i){const int row=i*8+(lane>>3),ch=lane&7; const u32x4 v=*(const u32x4*)(stg+row*64+ch*8); const u32x4 zv=zpre[i]; u32x4 ov;
;       #pragma unroll
;       for(int e=0;e<4;++e){ const float o0=__uint_as_float(v[e]<<16),o1=__uint_as_float(v[e]&0xffff0000u),z0=__uint_as_float(zv[e]<<16),z1=__uint_as_float(zv[e]&0xffff0000u);
;         ov[e]=cvtpk_s(o0*z0*__builtin_amdgcn_rcpf(1.f+__expf(-z0)),o1*z1*__builtin_amdgcn_rcpf(1.f+__expf(-z1))); }
;       if(!DRY||ov[0]==0x7fc12345u)ATTN_STORE16(Ow+(long)row*DM+ch*8,ov);} }
;   asm volatile("s_waitcnt lgkmcnt(0)\n\ts_barrier":::"memory");
; template <bool DRY> __device__ __forceinline__ void fox_phase(const Args& A, char* lds, int vcu, int G) {
;     ...
;         BAR_LDS();
;         u = __builtin_amdgcn_readfirstlane((int)lw[0]);
	v_and_b32_e32 v7, 0xffff0000, v2
	v_lshlrev_b32_e32 v8, 16, v2
	v_pk_mul_f32 v[6:7], v[8:9], v[6:7]
	v_lshlrev_b32_e32 v8, 16, v73
	v_pk_mul_f32 v[6:7], v[10:11], v[6:7]
	v_and_b32_e32 v11, 0xffff0000, v73
	v_mul_f32_e32 v2, 0xbfb8aa3b, v8
	v_exp_f32_e32 v9, v2
	v_mul_f32_e32 v2, 0xbfb8aa3b, v11
	v_exp_f32_e32 v10, v2
	v_cvt_pk_bf16_f32 v2, v6, v7
	v_add_f32_e32 v6, 1.0, v9
	v_rcp_f32_e32 v6, v6
	v_add_f32_e32 v7, 1.0, v10
	v_rcp_f32_e32 v7, v7
	v_and_b32_e32 v9, 0xffff0000, v3
	v_lshlrev_b32_e32 v10, 16, v3
	v_pk_mul_f32 v[8:9], v[10:11], v[8:9]
	v_and_b32_e32 v11, 0xffff0000, v74
	v_pk_mul_f32 v[6:7], v[6:7], v[8:9]
	v_lshlrev_b32_e32 v8, 16, v74
	v_mul_f32_e32 v3, 0xbfb8aa3b, v8
	v_exp_f32_e32 v9, v3
	v_mul_f32_e32 v3, 0xbfb8aa3b, v11
	v_exp_f32_e32 v10, v3
	v_cvt_pk_bf16_f32 v3, v6, v7
	v_add_f32_e32 v6, 1.0, v9
	v_rcp_f32_e32 v6, v6
	v_add_f32_e32 v7, 1.0, v10
	v_rcp_f32_e32 v7, v7
	v_and_b32_e32 v9, 0xffff0000, v4
	v_lshlrev_b32_e32 v10, 16, v4
	v_pk_mul_f32 v[8:9], v[10:11], v[8:9]
	v_and_b32_e32 v11, 0xffff0000, v75
	v_pk_mul_f32 v[6:7], v[6:7], v[8:9]
	v_lshlrev_b32_e32 v8, 16, v75
	v_mul_f32_e32 v4, 0xbfb8aa3b, v8
	v_exp_f32_e32 v9, v4
	v_mul_f32_e32 v4, 0xbfb8aa3b, v11
	v_exp_f32_e32 v10, v4
	v_cvt_pk_bf16_f32 v4, v6, v7
	v_add_f32_e32 v6, 1.0, v9
	v_rcp_f32_e32 v6, v6
	v_add_f32_e32 v7, 1.0, v10
	v_rcp_f32_e32 v7, v7
	v_and_b32_e32 v9, 0xffff0000, v5
	v_lshlrev_b32_e32 v10, 16, v5
	v_pk_mul_f32 v[8:9], v[10:11], v[8:9]
	s_cselect_b32 s8, s3, 0
	v_pk_mul_f32 v[6:7], v[6:7], v[8:9]
	v_and_b32_e32 v9, 0xffff0000, v68
	v_cvt_pk_bf16_f32 v5, v6, v7
	v_add_co_u32_e32 v6, vcc, s78, v0
	s_cselect_b32 s9, s19, 0
	s_nop 0
	v_addc_co_u32_e32 v7, vcc, 0, v1, vcc
	global_store_dwordx4 v[6:7], v[2:5], off
	v_lshlrev_b32_e32 v6, 16, v68
	s_nop 0
	v_mul_f32_e32 v2, 0xbfb8aa3b, v6
	v_exp_f32_e32 v7, v2
	v_mul_f32_e32 v2, 0xbfb8aa3b, v9
	v_exp_f32_e32 v8, v2
	ds_read_b128 v[2:5], v14 offset:53248
	v_add_f32_e32 v7, 1.0, v7
	v_rcp_f32_e32 v10, v7
	v_add_f32_e32 v7, 1.0, v8
	v_rcp_f32_e32 v11, v7
	s_waitcnt lgkmcnt(0)
	v_and_b32_e32 v7, 0xffff0000, v2
	v_lshlrev_b32_e32 v8, 16, v2
	v_pk_mul_f32 v[6:7], v[8:9], v[6:7]
	v_lshlrev_b32_e32 v8, 16, v69
	v_pk_mul_f32 v[6:7], v[10:11], v[6:7]
	v_and_b32_e32 v11, 0xffff0000, v69
	v_mul_f32_e32 v2, 0xbfb8aa3b, v8
	v_exp_f32_e32 v9, v2
	v_mul_f32_e32 v2, 0xbfb8aa3b, v11
	v_exp_f32_e32 v10, v2
	v_cvt_pk_bf16_f32 v2, v6, v7
	v_add_f32_e32 v6, 1.0, v9
	v_rcp_f32_e32 v6, v6
	v_add_f32_e32 v7, 1.0, v10
	v_rcp_f32_e32 v7, v7
	v_and_b32_e32 v9, 0xffff0000, v3
	v_lshlrev_b32_e32 v10, 16, v3
	v_pk_mul_f32 v[8:9], v[10:11], v[8:9]
	v_and_b32_e32 v11, 0xffff0000, v70
	v_pk_mul_f32 v[6:7], v[6:7], v[8:9]
	v_lshlrev_b32_e32 v8, 16, v70
	v_mul_f32_e32 v3, 0xbfb8aa3b, v8
	v_exp_f32_e32 v9, v3
	v_mul_f32_e32 v3, 0xbfb8aa3b, v11
	v_exp_f32_e32 v10, v3
	v_cvt_pk_bf16_f32 v3, v6, v7
	v_add_f32_e32 v6, 1.0, v9
	v_rcp_f32_e32 v6, v6
	v_add_f32_e32 v7, 1.0, v10
	v_rcp_f32_e32 v7, v7
	v_and_b32_e32 v9, 0xffff0000, v4
	v_lshlrev_b32_e32 v10, 16, v4
	v_pk_mul_f32 v[8:9], v[10:11], v[8:9]
	v_and_b32_e32 v11, 0xffff0000, v71
	v_pk_mul_f32 v[6:7], v[6:7], v[8:9]
	v_lshlrev_b32_e32 v8, 16, v71
	v_mul_f32_e32 v4, 0xbfb8aa3b, v8
	v_exp_f32_e32 v9, v4
	v_mul_f32_e32 v4, 0xbfb8aa3b, v11
	v_exp_f32_e32 v10, v4
	v_cvt_pk_bf16_f32 v4, v6, v7
	v_add_f32_e32 v6, 1.0, v9
	v_rcp_f32_e32 v6, v6
	v_add_f32_e32 v7, 1.0, v10
	v_rcp_f32_e32 v7, v7
	v_and_b32_e32 v9, 0xffff0000, v5
	v_lshlrev_b32_e32 v10, 16, v5
	v_pk_mul_f32 v[8:9], v[10:11], v[8:9]
	s_nop 0
	v_pk_mul_f32 v[6:7], v[6:7], v[8:9]
	v_and_b32_e32 v9, 0xffff0000, v64
	v_cvt_pk_bf16_f32 v5, v6, v7
	v_add_co_u32_e32 v6, vcc, s79, v0
	s_nop 1
	v_addc_co_u32_e32 v7, vcc, 0, v1, vcc
	global_store_dwordx4 v[6:7], v[2:5], off
	v_lshlrev_b32_e32 v6, 16, v64
	v_add_co_u32_e32 v0, vcc, s80, v0
	v_mul_f32_e32 v2, 0xbfb8aa3b, v6
	v_exp_f32_e32 v7, v2
	v_mul_f32_e32 v2, 0xbfb8aa3b, v9
	v_exp_f32_e32 v8, v2
	ds_read_b128 v[2:5], v14 offset:54272
	v_add_f32_e32 v7, 1.0, v7
	v_rcp_f32_e32 v10, v7
	v_add_f32_e32 v7, 1.0, v8
	v_rcp_f32_e32 v11, v7
	s_waitcnt lgkmcnt(0)
	v_and_b32_e32 v7, 0xffff0000, v2
	v_lshlrev_b32_e32 v8, 16, v2
	v_pk_mul_f32 v[6:7], v[8:9], v[6:7]
	v_lshlrev_b32_e32 v8, 16, v65
	v_pk_mul_f32 v[6:7], v[10:11], v[6:7]
	v_and_b32_e32 v11, 0xffff0000, v65
	v_mul_f32_e32 v2, 0xbfb8aa3b, v8
	v_exp_f32_e32 v9, v2
	v_mul_f32_e32 v2, 0xbfb8aa3b, v11
	v_exp_f32_e32 v10, v2
	v_cvt_pk_bf16_f32 v2, v6, v7
	v_add_f32_e32 v6, 1.0, v9
	v_rcp_f32_e32 v6, v6
	v_add_f32_e32 v7, 1.0, v10
	v_rcp_f32_e32 v7, v7
	v_and_b32_e32 v9, 0xffff0000, v3
	v_lshlrev_b32_e32 v10, 16, v3
	v_pk_mul_f32 v[8:9], v[10:11], v[8:9]
	v_and_b32_e32 v11, 0xffff0000, v66
	v_pk_mul_f32 v[6:7], v[6:7], v[8:9]
	v_lshlrev_b32_e32 v8, 16, v66
	v_mul_f32_e32 v3, 0xbfb8aa3b, v8
	v_exp_f32_e32 v9, v3
	v_mul_f32_e32 v3, 0xbfb8aa3b, v11
	v_exp_f32_e32 v10, v3
	v_cvt_pk_bf16_f32 v3, v6, v7
	v_add_f32_e32 v6, 1.0, v9
	v_rcp_f32_e32 v6, v6
	v_add_f32_e32 v7, 1.0, v10
	v_rcp_f32_e32 v7, v7
	v_and_b32_e32 v9, 0xffff0000, v4
	v_lshlrev_b32_e32 v10, 16, v4
	v_pk_mul_f32 v[8:9], v[10:11], v[8:9]
	v_and_b32_e32 v11, 0xffff0000, v67
	v_pk_mul_f32 v[6:7], v[6:7], v[8:9]
	v_lshlrev_b32_e32 v8, 16, v67
	v_mul_f32_e32 v4, 0xbfb8aa3b, v8
	v_exp_f32_e32 v9, v4
	v_mul_f32_e32 v4, 0xbfb8aa3b, v11
	v_exp_f32_e32 v10, v4
	v_cvt_pk_bf16_f32 v4, v6, v7
	v_add_f32_e32 v6, 1.0, v9
	v_rcp_f32_e32 v6, v6
	v_add_f32_e32 v7, 1.0, v10
	v_rcp_f32_e32 v7, v7
	v_and_b32_e32 v9, 0xffff0000, v5
	v_lshlrev_b32_e32 v10, 16, v5
	v_pk_mul_f32 v[8:9], v[10:11], v[8:9]
	v_addc_co_u32_e32 v1, vcc, 0, v1, vcc
	v_pk_mul_f32 v[6:7], v[6:7], v[8:9]
	s_nop 0
	v_cvt_pk_bf16_f32 v5, v6, v7
	global_store_dwordx4 v[0:1], v[2:5], off
	s_waitcnt lgkmcnt(0)
	s_barrier
	s_waitcnt lgkmcnt(0)
	s_barrier
	v_mov_b32_e32 v0, s8
	v_mov_b32_e32 v1, s9
	ds_read_b32 v0, v0
	s_waitcnt lgkmcnt(0)
	v_readfirstlane_b32 s10, v0
	s_cmpk_lt_i32 s10, 0x600
	s_cbranch_scc0 .LBB0_1531
